# k48 + the last FF1 unit of every workgroup stores its tile write-through (sc1) so the FF1->FF2 grid barrier's L2 writeback has less dirty data
# speedup vs baseline: 1.0241x; 1.0013x over previous
.LBB0_859:
	s_add_u32 s98, s10, 0x80
	s_addc_u32 s99, s11, 0
	v_lshl_add_u64 v[250:251], s[98:99], 0, v[136:137]
	s_add_i32 m0, s25, 0xc000
	s_nop 0
	global_load_lds_dwordx4 v[250:251], off
	v_lshl_add_u64 v[250:251], s[98:99], 0, v[138:139]
	s_add_i32 m0, s25, 0xe000
	s_nop 0
	global_load_lds_dwordx4 v[250:251], off
	s_cmp_eq_u32 s29, 4
	s_cbranch_scc1 .Lff1_epi_last
	v_lshl_add_u32 v152, s80, 8, v146
	v_lshl_or_b32 v144, s81, 8, v148
	v_ashrrev_i32_e32 v153, 31, v152
	v_max_f32_e32 v120, 0, v120
	v_ashrrev_i32_e32 v145, 31, v144
	v_lshlrev_b64 v[154:155], 13, v[152:153]
	v_max_f32_e32 v121, 0, v121
	v_max_f32_e32 v122, 0, v122
	v_max_f32_e32 v123, 0, v123
	v_lshl_add_u64 v[154:155], s[16:17], 0, v[154:155]
	v_lshlrev_b64 v[156:157], 1, v[144:145]
	v_max_f32_e32 v124, 0, v124
	v_mul_f32_e32 v120, v120, v120
	v_max_f32_e32 v125, 0, v125
	v_max_f32_e32 v126, 0, v126
	v_max_f32_e32 v127, 0, v127
	v_max_f32_e32 v112, 0, v112
	v_lshl_add_u64 v[144:145], v[154:155], 0, v[156:157]
	v_mul_f32_e32 v121, v121, v121
	v_mul_f32_e32 v122, v122, v122
	v_mul_f32_e32 v123, v123, v123
	v_cvt_pk_bf16_f32 v120, v120, v121
	v_max_f32_e32 v113, 0, v113
	v_max_f32_e32 v114, 0, v114
	v_mul_f32_e32 v124, v124, v124
	v_mul_f32_e32 v125, v125, v125
	v_mul_f32_e32 v126, v126, v126
	v_mul_f32_e32 v127, v127, v127
	v_cvt_pk_bf16_f32 v121, v122, v123
	v_cvt_pk_bf16_f32 v122, v124, v125
	v_cvt_pk_bf16_f32 v123, v126, v127
	global_store_dwordx4 v[144:145], v[120:123], off
	s_nop 1
	v_mul_f32_e32 v120, v112, v112
	v_max_f32_e32 v112, 0, v117
	v_max_f32_e32 v116, 0, v116
	v_mul_f32_e32 v117, v113, v113
	v_max_f32_e32 v113, 0, v118
	v_mul_f32_e32 v118, v114, v114
	v_max_f32_e32 v114, 0, v119
	v_max_f32_e32 v115, 0, v115
	v_mul_f32_e32 v112, v112, v112
	v_mul_f32_e32 v116, v116, v116
	v_mul_f32_e32 v113, v113, v113
	v_mul_f32_e32 v114, v114, v114
	v_mul_f32_e32 v115, v115, v115
	v_cvt_pk_bf16_f32 v112, v116, v112
	v_max_f32_e32 v104, 0, v104
	v_cvt_pk_bf16_f32 v113, v113, v114
	v_cvt_pk_bf16_f32 v114, v120, v117
	v_cvt_pk_bf16_f32 v115, v118, v115
	global_store_dwordx4 v[144:145], v[112:115], off offset:256
	s_nop 1
	v_max_f32_e32 v105, 0, v105
	v_or_b32_e32 v112, 16, v152
	v_max_f32_e32 v106, 0, v106
	v_ashrrev_i32_e32 v113, 31, v112
	v_mul_f32_e32 v114, v104, v104
	v_max_f32_e32 v104, 0, v109
	v_lshlrev_b64 v[112:113], 13, v[112:113]
	v_max_f32_e32 v108, 0, v108
	v_mul_f32_e32 v109, v105, v105
	v_max_f32_e32 v105, 0, v110
	v_mul_f32_e32 v110, v106, v106
	v_max_f32_e32 v106, 0, v111
	v_max_f32_e32 v107, 0, v107
	v_lshl_add_u64 v[112:113], s[16:17], 0, v[112:113]
	v_mul_f32_e32 v104, v104, v104
	v_max_f32_e32 v96, 0, v96
	v_lshl_add_u64 v[112:113], v[112:113], 0, v[156:157]
	v_mul_f32_e32 v108, v108, v108
	v_mul_f32_e32 v105, v105, v105
	v_mul_f32_e32 v106, v106, v106
	v_mul_f32_e32 v107, v107, v107
	v_cvt_pk_bf16_f32 v104, v108, v104
	v_max_f32_e32 v97, 0, v97
	v_max_f32_e32 v98, 0, v98
	v_cvt_pk_bf16_f32 v105, v105, v106
	v_cvt_pk_bf16_f32 v106, v114, v109
	v_cvt_pk_bf16_f32 v107, v110, v107
	global_store_dwordx4 v[112:113], v[104:107], off
	s_nop 1
	v_mul_f32_e32 v104, v96, v96
	v_max_f32_e32 v96, 0, v101
	v_max_f32_e32 v100, 0, v100
	v_mul_f32_e32 v101, v97, v97
	v_max_f32_e32 v97, 0, v102
	v_mul_f32_e32 v102, v98, v98
	v_max_f32_e32 v98, 0, v103
	v_max_f32_e32 v99, 0, v99
	v_mul_f32_e32 v96, v96, v96
	v_mul_f32_e32 v100, v100, v100
	v_mul_f32_e32 v97, v97, v97
	v_mul_f32_e32 v98, v98, v98
	v_mul_f32_e32 v99, v99, v99
	v_cvt_pk_bf16_f32 v96, v100, v96
	v_max_f32_e32 v88, 0, v88
	v_cvt_pk_bf16_f32 v97, v97, v98
	v_cvt_pk_bf16_f32 v98, v104, v101
	v_cvt_pk_bf16_f32 v99, v102, v99
	global_store_dwordx4 v[112:113], v[96:99], off offset:256
	s_nop 1
	v_max_f32_e32 v89, 0, v89
	v_or_b32_e32 v96, 32, v152
	v_max_f32_e32 v90, 0, v90
	v_ashrrev_i32_e32 v97, 31, v96
	v_mul_f32_e32 v98, v88, v88
	v_max_f32_e32 v88, 0, v93
	v_lshlrev_b64 v[96:97], 13, v[96:97]
	v_max_f32_e32 v92, 0, v92
	v_mul_f32_e32 v93, v89, v89
	v_max_f32_e32 v89, 0, v94
	v_mul_f32_e32 v94, v90, v90
	v_max_f32_e32 v90, 0, v95
	v_max_f32_e32 v91, 0, v91
	v_lshl_add_u64 v[96:97], s[16:17], 0, v[96:97]
	v_mul_f32_e32 v88, v88, v88
	v_max_f32_e32 v80, 0, v80
	v_lshl_add_u64 v[96:97], v[96:97], 0, v[156:157]
	v_mul_f32_e32 v92, v92, v92
	v_mul_f32_e32 v89, v89, v89
	v_mul_f32_e32 v90, v90, v90
	v_mul_f32_e32 v91, v91, v91
	v_cvt_pk_bf16_f32 v88, v92, v88
	v_max_f32_e32 v81, 0, v81
	v_max_f32_e32 v82, 0, v82
	v_cvt_pk_bf16_f32 v89, v89, v90
	v_cvt_pk_bf16_f32 v90, v98, v93
	v_cvt_pk_bf16_f32 v91, v94, v91
	global_store_dwordx4 v[96:97], v[88:91], off
	s_nop 1
	v_mul_f32_e32 v88, v80, v80
	v_max_f32_e32 v80, 0, v85
	v_max_f32_e32 v84, 0, v84
	v_mul_f32_e32 v85, v81, v81
	v_max_f32_e32 v81, 0, v86
	v_mul_f32_e32 v86, v82, v82
	v_max_f32_e32 v82, 0, v87
	v_max_f32_e32 v83, 0, v83
	v_mul_f32_e32 v80, v80, v80
	v_mul_f32_e32 v84, v84, v84
	v_mul_f32_e32 v81, v81, v81
	v_mul_f32_e32 v82, v82, v82
	v_mul_f32_e32 v83, v83, v83
	v_cvt_pk_bf16_f32 v80, v84, v80
	v_max_f32_e32 v72, 0, v72
	v_cvt_pk_bf16_f32 v81, v81, v82
	v_cvt_pk_bf16_f32 v82, v88, v85
	v_cvt_pk_bf16_f32 v83, v86, v83
	global_store_dwordx4 v[96:97], v[80:83], off offset:256
	s_nop 1
	v_max_f32_e32 v73, 0, v73
	v_or_b32_e32 v80, 48, v152
	v_max_f32_e32 v74, 0, v74
	v_ashrrev_i32_e32 v81, 31, v80
	v_mul_f32_e32 v82, v72, v72
	v_max_f32_e32 v72, 0, v77
	v_lshlrev_b64 v[80:81], 13, v[80:81]
	v_max_f32_e32 v76, 0, v76
	v_mul_f32_e32 v77, v73, v73
	v_max_f32_e32 v73, 0, v78
	v_mul_f32_e32 v78, v74, v74
	v_max_f32_e32 v74, 0, v79
	v_max_f32_e32 v75, 0, v75
	v_lshl_add_u64 v[80:81], s[16:17], 0, v[80:81]
	v_mul_f32_e32 v72, v72, v72
	v_max_f32_e32 v64, 0, v64
	v_max_f32_e32 v65, 0, v65
	v_max_f32_e32 v66, 0, v66
	v_lshl_add_u64 v[80:81], v[80:81], 0, v[156:157]
	v_mul_f32_e32 v76, v76, v76
	v_mul_f32_e32 v73, v73, v73
	v_mul_f32_e32 v74, v74, v74
	v_mul_f32_e32 v75, v75, v75
	v_cvt_pk_bf16_f32 v72, v76, v72
	v_cvt_pk_bf16_f32 v73, v73, v74
	v_cvt_pk_bf16_f32 v74, v82, v77
	v_cvt_pk_bf16_f32 v75, v78, v75
	global_store_dwordx4 v[80:81], v[72:75], off
	v_max_f32_e32 v68, 0, v68
	v_max_f32_e32 v67, 0, v67
	v_mul_f32_e32 v72, v64, v64
	v_max_f32_e32 v64, 0, v69
	v_mul_f32_e32 v69, v65, v65
	v_max_f32_e32 v65, 0, v70
	v_mul_f32_e32 v70, v66, v66
	v_max_f32_e32 v66, 0, v71
	v_mul_f32_e32 v64, v64, v64
	v_mul_f32_e32 v65, v65, v65
	v_mul_f32_e32 v66, v66, v66
	v_max_f32_e32 v56, 0, v56
	v_mul_f32_e32 v68, v68, v68
	v_mul_f32_e32 v67, v67, v67
	v_cvt_pk_bf16_f32 v64, v68, v64
	v_cvt_pk_bf16_f32 v65, v65, v66
	v_cvt_pk_bf16_f32 v66, v72, v69
	v_max_f32_e32 v57, 0, v57
	v_max_f32_e32 v58, 0, v58
	v_cvt_pk_bf16_f32 v67, v70, v67
	global_store_dwordx4 v[80:81], v[64:67], off offset:256
	s_nop 1
	v_max_f32_e32 v60, 0, v60
	v_mul_f32_e32 v66, v56, v56
	v_max_f32_e32 v56, 0, v61
	v_mul_f32_e32 v61, v57, v57
	v_max_f32_e32 v57, 0, v62
	v_mul_f32_e32 v62, v58, v58
	v_max_f32_e32 v58, 0, v63
	v_mul_f32_e32 v60, v60, v60
	v_mul_f32_e32 v56, v56, v56
	v_max_f32_e32 v59, 0, v59
	v_mul_f32_e32 v57, v57, v57
	v_mul_f32_e32 v58, v58, v58
	v_cvt_pk_bf16_f32 v56, v60, v56
	v_add_co_u32_e32 v60, vcc, s69, v144
	v_max_f32_e32 v48, 0, v48
	v_max_f32_e32 v49, 0, v49
	v_max_f32_e32 v50, 0, v50
	v_mul_f32_e32 v59, v59, v59
	v_cvt_pk_bf16_f32 v57, v57, v58
	v_cvt_pk_bf16_f32 v58, v66, v61
	v_addc_co_u32_e32 v61, vcc, 0, v145, vcc
	v_cvt_pk_bf16_f32 v59, v62, v59
	global_store_dwordx4 v[60:61], v[56:59], off
	v_max_f32_e32 v52, 0, v52
	v_max_f32_e32 v51, 0, v51
	v_mul_f32_e32 v56, v48, v48
	v_max_f32_e32 v48, 0, v53
	v_mul_f32_e32 v53, v49, v49
	v_max_f32_e32 v49, 0, v54
	v_mul_f32_e32 v54, v50, v50
	v_max_f32_e32 v50, 0, v55
	v_mul_f32_e32 v48, v48, v48
	v_mul_f32_e32 v49, v49, v49
	v_mul_f32_e32 v50, v50, v50
	v_max_f32_e32 v40, 0, v40
	v_lshl_add_u64 v[64:65], v[144:145], 0, s[50:51]
	v_mul_f32_e32 v52, v52, v52
	v_mul_f32_e32 v51, v51, v51
	v_cvt_pk_bf16_f32 v48, v52, v48
	v_cvt_pk_bf16_f32 v49, v49, v50
	v_cvt_pk_bf16_f32 v50, v56, v53
	v_max_f32_e32 v41, 0, v41
	v_max_f32_e32 v42, 0, v42
	v_cvt_pk_bf16_f32 v51, v54, v51
	global_store_dwordx4 v[64:65], v[48:51], off offset:256
	s_nop 1
	v_max_f32_e32 v44, 0, v44
	v_mul_f32_e32 v50, v40, v40
	v_max_f32_e32 v40, 0, v45
	v_mul_f32_e32 v45, v41, v41
	v_max_f32_e32 v41, 0, v46
	v_mul_f32_e32 v46, v42, v42
	v_max_f32_e32 v42, 0, v47
	v_mul_f32_e32 v44, v44, v44
	v_mul_f32_e32 v40, v40, v40
	v_max_f32_e32 v43, 0, v43
	v_mul_f32_e32 v41, v41, v41
	v_mul_f32_e32 v42, v42, v42
	v_cvt_pk_bf16_f32 v40, v44, v40
	v_add_co_u32_e32 v44, vcc, s71, v144
	v_max_f32_e32 v32, 0, v32
	v_max_f32_e32 v33, 0, v33
	v_max_f32_e32 v34, 0, v34
	v_mul_f32_e32 v43, v43, v43
	v_cvt_pk_bf16_f32 v41, v41, v42
	v_cvt_pk_bf16_f32 v42, v50, v45
	v_addc_co_u32_e32 v45, vcc, 0, v145, vcc
	v_cvt_pk_bf16_f32 v43, v46, v43
	global_store_dwordx4 v[44:45], v[40:43], off
	v_max_f32_e32 v36, 0, v36
	v_max_f32_e32 v35, 0, v35
	v_mul_f32_e32 v40, v32, v32
	v_max_f32_e32 v32, 0, v37
	v_mul_f32_e32 v37, v33, v33
	v_max_f32_e32 v33, 0, v38
	v_mul_f32_e32 v38, v34, v34
	v_max_f32_e32 v34, 0, v39
	v_mul_f32_e32 v32, v32, v32
	v_mul_f32_e32 v33, v33, v33
	v_mul_f32_e32 v34, v34, v34
	v_max_f32_e32 v24, 0, v24
	v_lshl_add_u64 v[48:49], v[144:145], 0, s[52:53]
	v_mul_f32_e32 v36, v36, v36
	v_mul_f32_e32 v35, v35, v35
	v_cvt_pk_bf16_f32 v32, v36, v32
	v_cvt_pk_bf16_f32 v33, v33, v34
	v_cvt_pk_bf16_f32 v34, v40, v37
	v_max_f32_e32 v25, 0, v25
	v_max_f32_e32 v26, 0, v26
	v_cvt_pk_bf16_f32 v35, v38, v35
	global_store_dwordx4 v[48:49], v[32:35], off offset:256
	s_nop 1
	v_max_f32_e32 v28, 0, v28
	v_mul_f32_e32 v34, v24, v24
	v_max_f32_e32 v24, 0, v29
	v_mul_f32_e32 v29, v25, v25
	v_max_f32_e32 v25, 0, v30
	v_mul_f32_e32 v30, v26, v26
	v_max_f32_e32 v26, 0, v31
	v_mul_f32_e32 v28, v28, v28
	v_mul_f32_e32 v24, v24, v24
	v_max_f32_e32 v27, 0, v27
	v_mul_f32_e32 v25, v25, v25
	v_mul_f32_e32 v26, v26, v26
	v_cvt_pk_bf16_f32 v24, v28, v24
	v_add_co_u32_e32 v28, vcc, s72, v144
	v_max_f32_e32 v16, 0, v16
	v_max_f32_e32 v17, 0, v17
	v_max_f32_e32 v18, 0, v18
	v_mul_f32_e32 v27, v27, v27
	v_cvt_pk_bf16_f32 v25, v25, v26
	v_cvt_pk_bf16_f32 v26, v34, v29
	v_addc_co_u32_e32 v29, vcc, 0, v145, vcc
	v_cvt_pk_bf16_f32 v27, v30, v27
	global_store_dwordx4 v[28:29], v[24:27], off
	v_max_f32_e32 v20, 0, v20
	v_max_f32_e32 v19, 0, v19
	v_mul_f32_e32 v24, v16, v16
	v_max_f32_e32 v16, 0, v21
	v_mul_f32_e32 v21, v17, v17
	v_max_f32_e32 v17, 0, v22
	v_mul_f32_e32 v22, v18, v18
	v_max_f32_e32 v18, 0, v23
	v_mul_f32_e32 v16, v16, v16
	v_mul_f32_e32 v17, v17, v17
	v_mul_f32_e32 v18, v18, v18
	v_max_f32_e32 v8, 0, v8
	v_lshl_add_u64 v[32:33], v[144:145], 0, s[54:55]
	v_mul_f32_e32 v20, v20, v20
	v_mul_f32_e32 v19, v19, v19
	v_cvt_pk_bf16_f32 v16, v20, v16
	v_cvt_pk_bf16_f32 v17, v17, v18
	v_cvt_pk_bf16_f32 v18, v24, v21
	v_max_f32_e32 v9, 0, v9
	v_max_f32_e32 v10, 0, v10
	v_cvt_pk_bf16_f32 v19, v22, v19
	global_store_dwordx4 v[32:33], v[16:19], off offset:256
	s_nop 1
	v_max_f32_e32 v12, 0, v12
	v_mul_f32_e32 v18, v8, v8
	v_max_f32_e32 v8, 0, v13
	v_mul_f32_e32 v13, v9, v9
	v_max_f32_e32 v9, 0, v14
	v_mul_f32_e32 v14, v10, v10
	v_max_f32_e32 v10, 0, v15
	v_mul_f32_e32 v12, v12, v12
	v_mul_f32_e32 v8, v8, v8
	v_max_f32_e32 v11, 0, v11
	v_mul_f32_e32 v9, v9, v9
	v_mul_f32_e32 v10, v10, v10
	v_cvt_pk_bf16_f32 v8, v12, v8
	v_add_co_u32_e32 v12, vcc, s75, v144
	v_max_f32_e32 v0, 0, v0
	v_max_f32_e32 v1, 0, v1
	v_max_f32_e32 v2, 0, v2
	v_mul_f32_e32 v11, v11, v11
	v_cvt_pk_bf16_f32 v9, v9, v10
	v_cvt_pk_bf16_f32 v10, v18, v13
	v_addc_co_u32_e32 v13, vcc, 0, v145, vcc
	v_cvt_pk_bf16_f32 v11, v14, v11
	global_store_dwordx4 v[12:13], v[8:11], off
	v_max_f32_e32 v3, 0, v3
	v_max_f32_e32 v4, 0, v4
	v_mul_f32_e32 v8, v0, v0
	v_max_f32_e32 v0, 0, v5
	v_mul_f32_e32 v5, v1, v1
	v_max_f32_e32 v1, 0, v6
	v_mul_f32_e32 v6, v2, v2
	v_max_f32_e32 v2, 0, v7
	v_lshl_add_u64 v[16:17], v[144:145], 0, s[56:57]
	v_mul_f32_e32 v0, v0, v0
	v_mul_f32_e32 v1, v1, v1
	v_mul_f32_e32 v2, v2, v2
	v_mul_f32_e32 v3, v3, v3
	s_and_b64 vcc, exec, s[8:9]
	s_mov_b64 s[8:9], -1
	v_mul_f32_e32 v4, v4, v4
	v_cvt_pk_bf16_f32 v0, v4, v0
	v_cvt_pk_bf16_f32 v1, v1, v2
	v_cvt_pk_bf16_f32 v2, v8, v5
	v_cvt_pk_bf16_f32 v3, v6, v3
	global_store_dwordx4 v[16:17], v[0:3], off offset:256
	s_branch .Lff1_epi_join
.Lff1_epi_last:
	v_lshl_add_u32 v152, s80, 8, v146
	v_lshl_or_b32 v144, s81, 8, v148
	v_ashrrev_i32_e32 v153, 31, v152
	v_max_f32_e32 v120, 0, v120
	v_ashrrev_i32_e32 v145, 31, v144
	v_lshlrev_b64 v[154:155], 13, v[152:153]
	v_max_f32_e32 v121, 0, v121
	v_max_f32_e32 v122, 0, v122
	v_max_f32_e32 v123, 0, v123
	v_lshl_add_u64 v[154:155], s[16:17], 0, v[154:155]
	v_lshlrev_b64 v[156:157], 1, v[144:145]
	v_max_f32_e32 v124, 0, v124
	v_mul_f32_e32 v120, v120, v120
	v_max_f32_e32 v125, 0, v125
	v_max_f32_e32 v126, 0, v126
	v_max_f32_e32 v127, 0, v127
	v_max_f32_e32 v112, 0, v112
	v_lshl_add_u64 v[144:145], v[154:155], 0, v[156:157]
	v_mul_f32_e32 v121, v121, v121
	v_mul_f32_e32 v122, v122, v122
	v_mul_f32_e32 v123, v123, v123
	v_cvt_pk_bf16_f32 v120, v120, v121
	v_max_f32_e32 v113, 0, v113
	v_max_f32_e32 v114, 0, v114
	v_mul_f32_e32 v124, v124, v124
	v_mul_f32_e32 v125, v125, v125
	v_mul_f32_e32 v126, v126, v126
	v_mul_f32_e32 v127, v127, v127
	v_cvt_pk_bf16_f32 v121, v122, v123
	v_cvt_pk_bf16_f32 v122, v124, v125
	v_cvt_pk_bf16_f32 v123, v126, v127
	global_store_dwordx4 v[144:145], v[120:123], off sc1
	s_nop 1
	v_mul_f32_e32 v120, v112, v112
	v_max_f32_e32 v112, 0, v117
	v_max_f32_e32 v116, 0, v116
	v_mul_f32_e32 v117, v113, v113
	v_max_f32_e32 v113, 0, v118
	v_mul_f32_e32 v118, v114, v114
	v_max_f32_e32 v114, 0, v119
	v_max_f32_e32 v115, 0, v115
	v_mul_f32_e32 v112, v112, v112
	v_mul_f32_e32 v116, v116, v116
	v_mul_f32_e32 v113, v113, v113
	v_mul_f32_e32 v114, v114, v114
	v_mul_f32_e32 v115, v115, v115
	v_cvt_pk_bf16_f32 v112, v116, v112
	v_max_f32_e32 v104, 0, v104
	v_cvt_pk_bf16_f32 v113, v113, v114
	v_cvt_pk_bf16_f32 v114, v120, v117
	v_cvt_pk_bf16_f32 v115, v118, v115
	global_store_dwordx4 v[144:145], v[112:115], off offset:256 sc1
	s_nop 1
	v_max_f32_e32 v105, 0, v105
	v_or_b32_e32 v112, 16, v152
	v_max_f32_e32 v106, 0, v106
	v_ashrrev_i32_e32 v113, 31, v112
	v_mul_f32_e32 v114, v104, v104
	v_max_f32_e32 v104, 0, v109
	v_lshlrev_b64 v[112:113], 13, v[112:113]
	v_max_f32_e32 v108, 0, v108
	v_mul_f32_e32 v109, v105, v105
	v_max_f32_e32 v105, 0, v110
	v_mul_f32_e32 v110, v106, v106
	v_max_f32_e32 v106, 0, v111
	v_max_f32_e32 v107, 0, v107
	v_lshl_add_u64 v[112:113], s[16:17], 0, v[112:113]
	v_mul_f32_e32 v104, v104, v104
	v_max_f32_e32 v96, 0, v96
	v_lshl_add_u64 v[112:113], v[112:113], 0, v[156:157]
	v_mul_f32_e32 v108, v108, v108
	v_mul_f32_e32 v105, v105, v105
	v_mul_f32_e32 v106, v106, v106
	v_mul_f32_e32 v107, v107, v107
	v_cvt_pk_bf16_f32 v104, v108, v104
	v_max_f32_e32 v97, 0, v97
	v_max_f32_e32 v98, 0, v98
	v_cvt_pk_bf16_f32 v105, v105, v106
	v_cvt_pk_bf16_f32 v106, v114, v109
	v_cvt_pk_bf16_f32 v107, v110, v107
	global_store_dwordx4 v[112:113], v[104:107], off sc1
	s_nop 1
	v_mul_f32_e32 v104, v96, v96
	v_max_f32_e32 v96, 0, v101
	v_max_f32_e32 v100, 0, v100
	v_mul_f32_e32 v101, v97, v97
	v_max_f32_e32 v97, 0, v102
	v_mul_f32_e32 v102, v98, v98
	v_max_f32_e32 v98, 0, v103
	v_max_f32_e32 v99, 0, v99
	v_mul_f32_e32 v96, v96, v96
	v_mul_f32_e32 v100, v100, v100
	v_mul_f32_e32 v97, v97, v97
	v_mul_f32_e32 v98, v98, v98
	v_mul_f32_e32 v99, v99, v99
	v_cvt_pk_bf16_f32 v96, v100, v96
	v_max_f32_e32 v88, 0, v88
	v_cvt_pk_bf16_f32 v97, v97, v98
	v_cvt_pk_bf16_f32 v98, v104, v101
	v_cvt_pk_bf16_f32 v99, v102, v99
	global_store_dwordx4 v[112:113], v[96:99], off offset:256 sc1
	s_nop 1
	v_max_f32_e32 v89, 0, v89
	v_or_b32_e32 v96, 32, v152
	v_max_f32_e32 v90, 0, v90
	v_ashrrev_i32_e32 v97, 31, v96
	v_mul_f32_e32 v98, v88, v88
	v_max_f32_e32 v88, 0, v93
	v_lshlrev_b64 v[96:97], 13, v[96:97]
	v_max_f32_e32 v92, 0, v92
	v_mul_f32_e32 v93, v89, v89
	v_max_f32_e32 v89, 0, v94
	v_mul_f32_e32 v94, v90, v90
	v_max_f32_e32 v90, 0, v95
	v_max_f32_e32 v91, 0, v91
	v_lshl_add_u64 v[96:97], s[16:17], 0, v[96:97]
	v_mul_f32_e32 v88, v88, v88
	v_max_f32_e32 v80, 0, v80
	v_lshl_add_u64 v[96:97], v[96:97], 0, v[156:157]
	v_mul_f32_e32 v92, v92, v92
	v_mul_f32_e32 v89, v89, v89
	v_mul_f32_e32 v90, v90, v90
	v_mul_f32_e32 v91, v91, v91
	v_cvt_pk_bf16_f32 v88, v92, v88
	v_max_f32_e32 v81, 0, v81
	v_max_f32_e32 v82, 0, v82
	v_cvt_pk_bf16_f32 v89, v89, v90
	v_cvt_pk_bf16_f32 v90, v98, v93
	v_cvt_pk_bf16_f32 v91, v94, v91
	global_store_dwordx4 v[96:97], v[88:91], off sc1
	s_nop 1
	v_mul_f32_e32 v88, v80, v80
	v_max_f32_e32 v80, 0, v85
	v_max_f32_e32 v84, 0, v84
	v_mul_f32_e32 v85, v81, v81
	v_max_f32_e32 v81, 0, v86
	v_mul_f32_e32 v86, v82, v82
	v_max_f32_e32 v82, 0, v87
	v_max_f32_e32 v83, 0, v83
	v_mul_f32_e32 v80, v80, v80
	v_mul_f32_e32 v84, v84, v84
	v_mul_f32_e32 v81, v81, v81
	v_mul_f32_e32 v82, v82, v82
	v_mul_f32_e32 v83, v83, v83
	v_cvt_pk_bf16_f32 v80, v84, v80
	v_max_f32_e32 v72, 0, v72
	v_cvt_pk_bf16_f32 v81, v81, v82
	v_cvt_pk_bf16_f32 v82, v88, v85
	v_cvt_pk_bf16_f32 v83, v86, v83
	global_store_dwordx4 v[96:97], v[80:83], off offset:256 sc1
	s_nop 1
	v_max_f32_e32 v73, 0, v73
	v_or_b32_e32 v80, 48, v152
	v_max_f32_e32 v74, 0, v74
	v_ashrrev_i32_e32 v81, 31, v80
	v_mul_f32_e32 v82, v72, v72
	v_max_f32_e32 v72, 0, v77
	v_lshlrev_b64 v[80:81], 13, v[80:81]
	v_max_f32_e32 v76, 0, v76
	v_mul_f32_e32 v77, v73, v73
	v_max_f32_e32 v73, 0, v78
	v_mul_f32_e32 v78, v74, v74
	v_max_f32_e32 v74, 0, v79
	v_max_f32_e32 v75, 0, v75
	v_lshl_add_u64 v[80:81], s[16:17], 0, v[80:81]
	v_mul_f32_e32 v72, v72, v72
	v_max_f32_e32 v64, 0, v64
	v_max_f32_e32 v65, 0, v65
	v_max_f32_e32 v66, 0, v66
	v_lshl_add_u64 v[80:81], v[80:81], 0, v[156:157]
	v_mul_f32_e32 v76, v76, v76
	v_mul_f32_e32 v73, v73, v73
	v_mul_f32_e32 v74, v74, v74
	v_mul_f32_e32 v75, v75, v75
	v_cvt_pk_bf16_f32 v72, v76, v72
	v_cvt_pk_bf16_f32 v73, v73, v74
	v_cvt_pk_bf16_f32 v74, v82, v77
	v_cvt_pk_bf16_f32 v75, v78, v75
	global_store_dwordx4 v[80:81], v[72:75], off sc1
	v_max_f32_e32 v68, 0, v68
	v_max_f32_e32 v67, 0, v67
	v_mul_f32_e32 v72, v64, v64
	v_max_f32_e32 v64, 0, v69
	v_mul_f32_e32 v69, v65, v65
	v_max_f32_e32 v65, 0, v70
	v_mul_f32_e32 v70, v66, v66
	v_max_f32_e32 v66, 0, v71
	v_mul_f32_e32 v64, v64, v64
	v_mul_f32_e32 v65, v65, v65
	v_mul_f32_e32 v66, v66, v66
	v_max_f32_e32 v56, 0, v56
	v_mul_f32_e32 v68, v68, v68
	v_mul_f32_e32 v67, v67, v67
	v_cvt_pk_bf16_f32 v64, v68, v64
	v_cvt_pk_bf16_f32 v65, v65, v66
	v_cvt_pk_bf16_f32 v66, v72, v69
	v_max_f32_e32 v57, 0, v57
	v_max_f32_e32 v58, 0, v58
	v_cvt_pk_bf16_f32 v67, v70, v67
	global_store_dwordx4 v[80:81], v[64:67], off offset:256 sc1
	s_nop 1
	v_max_f32_e32 v60, 0, v60
	v_mul_f32_e32 v66, v56, v56
	v_max_f32_e32 v56, 0, v61
	v_mul_f32_e32 v61, v57, v57
	v_max_f32_e32 v57, 0, v62
	v_mul_f32_e32 v62, v58, v58
	v_max_f32_e32 v58, 0, v63
	v_mul_f32_e32 v60, v60, v60
	v_mul_f32_e32 v56, v56, v56
	v_max_f32_e32 v59, 0, v59
	v_mul_f32_e32 v57, v57, v57
	v_mul_f32_e32 v58, v58, v58
	v_cvt_pk_bf16_f32 v56, v60, v56
	v_add_co_u32_e32 v60, vcc, s69, v144
	v_max_f32_e32 v48, 0, v48
	v_max_f32_e32 v49, 0, v49
	v_max_f32_e32 v50, 0, v50
	v_mul_f32_e32 v59, v59, v59
	v_cvt_pk_bf16_f32 v57, v57, v58
	v_cvt_pk_bf16_f32 v58, v66, v61
	v_addc_co_u32_e32 v61, vcc, 0, v145, vcc
	v_cvt_pk_bf16_f32 v59, v62, v59
	global_store_dwordx4 v[60:61], v[56:59], off sc1
	v_max_f32_e32 v52, 0, v52
	v_max_f32_e32 v51, 0, v51
	v_mul_f32_e32 v56, v48, v48
	v_max_f32_e32 v48, 0, v53
	v_mul_f32_e32 v53, v49, v49
	v_max_f32_e32 v49, 0, v54
	v_mul_f32_e32 v54, v50, v50
	v_max_f32_e32 v50, 0, v55
	v_mul_f32_e32 v48, v48, v48
	v_mul_f32_e32 v49, v49, v49
	v_mul_f32_e32 v50, v50, v50
	v_max_f32_e32 v40, 0, v40
	v_lshl_add_u64 v[64:65], v[144:145], 0, s[50:51]
	v_mul_f32_e32 v52, v52, v52
	v_mul_f32_e32 v51, v51, v51
	v_cvt_pk_bf16_f32 v48, v52, v48
	v_cvt_pk_bf16_f32 v49, v49, v50
	v_cvt_pk_bf16_f32 v50, v56, v53
	v_max_f32_e32 v41, 0, v41
	v_max_f32_e32 v42, 0, v42
	v_cvt_pk_bf16_f32 v51, v54, v51
	global_store_dwordx4 v[64:65], v[48:51], off offset:256 sc1
	s_nop 1
	v_max_f32_e32 v44, 0, v44
	v_mul_f32_e32 v50, v40, v40
	v_max_f32_e32 v40, 0, v45
	v_mul_f32_e32 v45, v41, v41
	v_max_f32_e32 v41, 0, v46
	v_mul_f32_e32 v46, v42, v42
	v_max_f32_e32 v42, 0, v47
	v_mul_f32_e32 v44, v44, v44
	v_mul_f32_e32 v40, v40, v40
	v_max_f32_e32 v43, 0, v43
	v_mul_f32_e32 v41, v41, v41
	v_mul_f32_e32 v42, v42, v42
	v_cvt_pk_bf16_f32 v40, v44, v40
	v_add_co_u32_e32 v44, vcc, s71, v144
	v_max_f32_e32 v32, 0, v32
	v_max_f32_e32 v33, 0, v33
	v_max_f32_e32 v34, 0, v34
	v_mul_f32_e32 v43, v43, v43
	v_cvt_pk_bf16_f32 v41, v41, v42
	v_cvt_pk_bf16_f32 v42, v50, v45
	v_addc_co_u32_e32 v45, vcc, 0, v145, vcc
	v_cvt_pk_bf16_f32 v43, v46, v43
	global_store_dwordx4 v[44:45], v[40:43], off sc1
	v_max_f32_e32 v36, 0, v36
	v_max_f32_e32 v35, 0, v35
	v_mul_f32_e32 v40, v32, v32
	v_max_f32_e32 v32, 0, v37
	v_mul_f32_e32 v37, v33, v33
	v_max_f32_e32 v33, 0, v38
	v_mul_f32_e32 v38, v34, v34
	v_max_f32_e32 v34, 0, v39
	v_mul_f32_e32 v32, v32, v32
	v_mul_f32_e32 v33, v33, v33
	v_mul_f32_e32 v34, v34, v34
	v_max_f32_e32 v24, 0, v24
	v_lshl_add_u64 v[48:49], v[144:145], 0, s[52:53]
	v_mul_f32_e32 v36, v36, v36
	v_mul_f32_e32 v35, v35, v35
	v_cvt_pk_bf16_f32 v32, v36, v32
	v_cvt_pk_bf16_f32 v33, v33, v34
	v_cvt_pk_bf16_f32 v34, v40, v37
	v_max_f32_e32 v25, 0, v25
	v_max_f32_e32 v26, 0, v26
	v_cvt_pk_bf16_f32 v35, v38, v35
	global_store_dwordx4 v[48:49], v[32:35], off offset:256 sc1
	s_nop 1
	v_max_f32_e32 v28, 0, v28
	v_mul_f32_e32 v34, v24, v24
	v_max_f32_e32 v24, 0, v29
	v_mul_f32_e32 v29, v25, v25
	v_max_f32_e32 v25, 0, v30
	v_mul_f32_e32 v30, v26, v26
	v_max_f32_e32 v26, 0, v31
	v_mul_f32_e32 v28, v28, v28
	v_mul_f32_e32 v24, v24, v24
	v_max_f32_e32 v27, 0, v27
	v_mul_f32_e32 v25, v25, v25
	v_mul_f32_e32 v26, v26, v26
	v_cvt_pk_bf16_f32 v24, v28, v24
	v_add_co_u32_e32 v28, vcc, s72, v144
	v_max_f32_e32 v16, 0, v16
	v_max_f32_e32 v17, 0, v17
	v_max_f32_e32 v18, 0, v18
	v_mul_f32_e32 v27, v27, v27
	v_cvt_pk_bf16_f32 v25, v25, v26
	v_cvt_pk_bf16_f32 v26, v34, v29
	v_addc_co_u32_e32 v29, vcc, 0, v145, vcc
	v_cvt_pk_bf16_f32 v27, v30, v27
	global_store_dwordx4 v[28:29], v[24:27], off sc1
	v_max_f32_e32 v20, 0, v20
	v_max_f32_e32 v19, 0, v19
	v_mul_f32_e32 v24, v16, v16
	v_max_f32_e32 v16, 0, v21
	v_mul_f32_e32 v21, v17, v17
	v_max_f32_e32 v17, 0, v22
	v_mul_f32_e32 v22, v18, v18
	v_max_f32_e32 v18, 0, v23
	v_mul_f32_e32 v16, v16, v16
	v_mul_f32_e32 v17, v17, v17
	v_mul_f32_e32 v18, v18, v18
	v_max_f32_e32 v8, 0, v8
	v_lshl_add_u64 v[32:33], v[144:145], 0, s[54:55]
	v_mul_f32_e32 v20, v20, v20
	v_mul_f32_e32 v19, v19, v19
	v_cvt_pk_bf16_f32 v16, v20, v16
	v_cvt_pk_bf16_f32 v17, v17, v18
	v_cvt_pk_bf16_f32 v18, v24, v21
	v_max_f32_e32 v9, 0, v9
	v_max_f32_e32 v10, 0, v10
	v_cvt_pk_bf16_f32 v19, v22, v19
	global_store_dwordx4 v[32:33], v[16:19], off offset:256 sc1
	s_nop 1
	v_max_f32_e32 v12, 0, v12
	v_mul_f32_e32 v18, v8, v8
	v_max_f32_e32 v8, 0, v13
	v_mul_f32_e32 v13, v9, v9
	v_max_f32_e32 v9, 0, v14
	v_mul_f32_e32 v14, v10, v10
	v_max_f32_e32 v10, 0, v15
	v_mul_f32_e32 v12, v12, v12
	v_mul_f32_e32 v8, v8, v8
	v_max_f32_e32 v11, 0, v11
	v_mul_f32_e32 v9, v9, v9
	v_mul_f32_e32 v10, v10, v10
	v_cvt_pk_bf16_f32 v8, v12, v8
	v_add_co_u32_e32 v12, vcc, s75, v144
	v_max_f32_e32 v0, 0, v0
	v_max_f32_e32 v1, 0, v1
	v_max_f32_e32 v2, 0, v2
	v_mul_f32_e32 v11, v11, v11
	v_cvt_pk_bf16_f32 v9, v9, v10
	v_cvt_pk_bf16_f32 v10, v18, v13
	v_addc_co_u32_e32 v13, vcc, 0, v145, vcc
	v_cvt_pk_bf16_f32 v11, v14, v11
	global_store_dwordx4 v[12:13], v[8:11], off sc1
	v_max_f32_e32 v3, 0, v3
	v_max_f32_e32 v4, 0, v4
	v_mul_f32_e32 v8, v0, v0
	v_max_f32_e32 v0, 0, v5
	v_mul_f32_e32 v5, v1, v1
	v_max_f32_e32 v1, 0, v6
	v_mul_f32_e32 v6, v2, v2
	v_max_f32_e32 v2, 0, v7
	v_lshl_add_u64 v[16:17], v[144:145], 0, s[56:57]
	v_mul_f32_e32 v0, v0, v0
	v_mul_f32_e32 v1, v1, v1
	v_mul_f32_e32 v2, v2, v2
	v_mul_f32_e32 v3, v3, v3
	s_and_b64 vcc, exec, s[8:9]
	s_mov_b64 s[8:9], -1
	v_mul_f32_e32 v4, v4, v4
	v_cvt_pk_bf16_f32 v0, v4, v0
	v_cvt_pk_bf16_f32 v1, v1, v2
	v_cvt_pk_bf16_f32 v2, v8, v5
	v_cvt_pk_bf16_f32 v3, v6, v3
	global_store_dwordx4 v[16:17], v[0:3], off offset:256 sc1
.Lff1_epi_join:
	s_cbranch_vccnz .LBB0_843
	s_andn2_b64 vcc, exec, s[42:43]
	s_cbranch_vccnz .LBB0_842
	s_barrier
	s_branch .LBB0_842
